# weight-conversion loops with a gain vector: gain multiply of the prefetched tile deferred to the end of the trip so the prefetch overlaps the transposition
# speedup vs baseline: 1.0068x; 1.0022x over previous
; DI unsigned pk2(float lo, float hi) { return (unsigned)f2bf(lo) | ((unsigned)f2bf(hi) << 16); }
;     DI bf16_t* z() const { return (bf16_t*)(ws + WS_Z); }
;     DI float* b1(int l, int v) const { return (float*)(ws + WS_B1) + (l * 2 + v) * 128; }
; template <class Map>
; DI void wconv(const float* __restrict__ W, int K, int Nsrc, const float* __restrict__ gain, bf16_t* __restrict__ dst, int Ndst, Map map, float* tile) {
;     ...
;     for (;;) {
;         const int nit = it + gridDim.x;
;         __syncthreads();
; #pragma unroll
;         for (int e = 0; e < 4; ++e) { tile[kk0 * 65 + nn4 + e] = a0[e]; tile[(kk0 + 32) * 65 + nn4 + e] = a1[e]; }
;         if (nit < ntiles) WCONV_LOAD(nit, b0, b1);
;         __syncthreads();
;         { const int kt = it % nkt, nt = it / nkt, k0 = kt * 64, n0 = nt * 64;
;           const float* tp = tile + (8 * cw) * 65 + nw;
;           u32x4 w; w.x = pk2(tp[0], tp[65]); w.y = pk2(tp[2 * 65], tp[3 * 65]); w.z = pk2(tp[4 * 65], tp[5 * 65]); w.w = pk2(tp[6 * 65], tp[7 * 65]);
;           *(u32x4*)(dst + (size_t)(n0 + nw) * K + k0 + 8 * cw) = w; }
;         if (nit >= ntiles) break;
;         a0 = b0; a1 = b1; it = nit;
;     }
.LBB0_1917:
	s_waitcnt lgkmcnt(0)
	s_barrier
	ds_read2_b32 v[10:11], v22 offset1:65
	ds_read2_b32 v[12:13], v22 offset0:130 offset1:195
	s_ashr_i32 s16, s63, 31
	s_lshr_b32 s16, s16, 28
	s_add_i32 s16, s63, s16
	s_waitcnt lgkmcnt(1)
	v_bfe_u32 v0, v10, 16, 1
	v_add3_u32 v0, v10, v0, s12
	v_bfe_u32 v10, v11, 16, 1
	v_lshrrev_b32_e32 v0, 16, v0
	v_add3_u32 v10, v11, v10, s12
	v_and_or_b32 v10, v10, s15, v0
	s_waitcnt lgkmcnt(0)
	v_bfe_u32 v0, v12, 16, 1
	v_add3_u32 v0, v12, v0, s12
	v_add_u32_e32 v12, 0x400, v22
	ds_read2_b32 v[14:15], v12 offset0:4 offset1:69
	v_bfe_u32 v11, v13, 16, 1
	ds_read2_b32 v[16:17], v12 offset0:134 offset1:199
	v_lshrrev_b32_e32 v0, 16, v0
	v_add3_u32 v11, v13, v11, s12
	s_ashr_i32 s17, s16, 4
	v_and_or_b32 v11, v11, s15, v0
	s_waitcnt lgkmcnt(1)
	v_bfe_u32 v0, v14, 16, 1
	v_add3_u32 v0, v14, v0, s12
	v_bfe_u32 v12, v15, 16, 1
	v_lshl_add_u32 v14, s17, 6, v21
	s_lshl_b32 s16, s17, 10
	v_lshrrev_b32_e32 v0, 16, v0
	v_add3_u32 v12, v15, v12, s12
	v_ashrrev_i32_e32 v15, 31, v14
	s_sub_i32 s16, s55, s16
	v_and_or_b32 v12, v12, s15, v0
	s_waitcnt lgkmcnt(0)
	v_bfe_u32 v0, v16, 16, 1
	v_lshlrev_b64 v[14:15], 11, v[14:15]
	v_add3_u32 v0, v16, v0, s12
	v_bfe_u32 v13, v17, 16, 1
	v_lshl_add_u64 v[14:15], s[52:53], 0, v[14:15]
	s_ashr_i32 s17, s16, 31
	v_lshrrev_b32_e32 v0, 16, v0
	v_add3_u32 v13, v17, v13, s12
	v_lshl_add_u64 v[14:15], s[16:17], 1, v[14:15]
	v_mov_b32_e32 v19, v1
	v_and_or_b32 v13, v13, s15, v0
	v_lshl_add_u64 v[14:15], v[14:15], 0, v[18:19]
	s_add_i32 s55, s55, s23
	global_store_dwordx4 v[14:15], v[10:13], off
	s_cmpk_lt_i32 s62, 0x200
	s_mov_b32 s63, s62
	s_waitcnt vmcnt(1)
	v_pk_mul_f32 v[8:9], v[8:9], v[28:29] op_sel_hi:[1,0]
	v_pk_mul_f32 v[6:7], v[6:7], v[28:29] op_sel_hi:[1,0]
	v_pk_mul_f32 v[4:5], v[4:5], v[30:31] op_sel_hi:[1,0]
	v_pk_mul_f32 v[2:3], v[2:3], v[30:31] op_sel_hi:[1,0]
	v_mov_b32_e32 v10, v2
	v_mov_b32_e32 v11, v3
	v_mov_b32_e32 v12, v4
	v_mov_b32_e32 v13, v5
	v_mov_b32_e32 v14, v6
	v_mov_b32_e32 v15, v7
	v_mov_b32_e32 v16, v8
	v_mov_b32_e32 v17, v9
	s_cbranch_scc0 .LBB0_1960

.LBB0_1957:
	s_or_b64 exec, exec, s[56:57]
	v_cmp_lt_i32_e32 vcc, -1, v0
	v_mov_b32_e32 v28, 1.0
	v_mov_b32_e32 v30, 1.0
	v_mov_b32_e32 v9, 0
	v_mov_b32_e32 v8, 0
	v_mov_b32_e32 v7, 0
	v_mov_b32_e32 v6, 0
	v_mov_b32_e32 v5, 0
	v_mov_b32_e32 v4, 0
	v_mov_b32_e32 v3, 0
	v_mov_b32_e32 v2, 0
	s_and_saveexec_b64 s[16:17], vcc
	s_cbranch_execz .LBB0_1916
	v_add_u32_e32 v2, s55, v24
	s_lshl_b32 s24, s64, 10
	v_subrev_u32_e32 v10, s24, v2
	v_mov_b64_e32 v[2:3], s[48:49]
	v_lshlrev_b64 v[6:7], 2, v[0:1]
	v_add_u32_e32 v0, 32, v10
	v_mad_i64_i32 v[4:5], s[24:25], v10, s95, v[2:3]
	v_mad_i64_i32 v[2:3], s[24:25], v0, s95, v[2:3]
	v_lshl_add_u64 v[4:5], v[4:5], 0, v[6:7]
	v_lshl_add_u64 v[2:3], v[2:3], 0, v[6:7]
	global_load_dwordx4 v[6:9], v[4:5], off
	s_nop 0
	global_load_dwordx4 v[2:5], v[2:3], off
	s_and_b64 vcc, exec, s[42:43]
	s_cbranch_vccnz .LBB0_1916
	v_ashrrev_i32_e32 v11, 31, v10
	v_lshl_add_u64 v[10:11], v[10:11], 2, s[50:51]
	global_load_dword v28, v[10:11], off
	s_nop 0
	global_load_dword v30, v[10:11], off offset:128
	s_branch .LBB0_1916

; DI unsigned pk2(float lo, float hi) { return (unsigned)f2bf(lo) | ((unsigned)f2bf(hi) << 16); }
;     DI bf16_t* z() const { return (bf16_t*)(ws + WS_Z); }
;     DI float* b1(int l, int v) const { return (float*)(ws + WS_B1) + (l * 2 + v) * 128; }
; template <class Map>
; DI void wconv(const float* __restrict__ W, int K, int Nsrc, const float* __restrict__ gain, bf16_t* __restrict__ dst, int Ndst, Map map, float* tile) {
;     ...
;     WCONV_LOAD(it, a0, a1);
;     for (;;) {
;         const int nit = it + gridDim.x;
;         __syncthreads();
; #pragma unroll
;         for (int e = 0; e < 4; ++e) { tile[kk0 * 65 + nn4 + e] = a0[e]; tile[(kk0 + 32) * 65 + nn4 + e] = a1[e]; }
;         if (nit < ntiles) WCONV_LOAD(nit, b0, b1);
;         __syncthreads();
;         { const int kt = it % nkt, nt = it / nkt, k0 = kt * 64, n0 = nt * 64;
;           const float* tp = tile + (8 * cw) * 65 + nw;
;           u32x4 w; w.x = pk2(tp[0], tp[65]); w.y = pk2(tp[2 * 65], tp[3 * 65]); w.z = pk2(tp[4 * 65], tp[5 * 65]); w.w = pk2(tp[6 * 65], tp[7 * 65]);
;           *(u32x4*)(dst + (size_t)(n0 + nw) * K + k0 + 8 * cw) = w; }
;         if (nit >= ntiles) break;
;         a0 = b0; a1 = b1; it = nit;
;     }
.LBB0_1970:
	s_waitcnt lgkmcnt(0)
	s_barrier
	ds_read2_b32 v[10:11], v20 offset1:65
	s_mul_hi_i32 s16, s60, 0x2aaaaaab
	s_lshr_b32 s17, s16, 31
	s_add_i32 s17, s16, s17
	s_mul_i32 s16, s17, 0xfffffe80
	s_waitcnt lgkmcnt(0)
	v_bfe_u32 v12, v10, 16, 1
	v_add3_u32 v10, v10, v12, s12
	ds_read2_b32 v[12:13], v20 offset0:130 offset1:195
	v_bfe_u32 v14, v11, 16, 1
	v_lshrrev_b32_e32 v10, 16, v10
	v_add3_u32 v11, v11, v14, s12
	v_and_or_b32 v10, v11, s15, v10
	s_waitcnt lgkmcnt(0)
	v_bfe_u32 v11, v12, 16, 1
	v_add3_u32 v11, v12, v11, s12
	v_add_u32_e32 v12, 0x400, v20
	ds_read2_b32 v[14:15], v12 offset0:4 offset1:69
	v_bfe_u32 v16, v13, 16, 1
	v_lshrrev_b32_e32 v11, 16, v11
	v_add3_u32 v13, v13, v16, s12
	ds_read2_b32 v[16:17], v12 offset0:134 offset1:199
	v_and_or_b32 v11, v13, s15, v11
	s_waitcnt lgkmcnt(1)
	v_bfe_u32 v13, v14, 16, 1
	v_add3_u32 v13, v14, v13, s12
	v_lshrrev_b32_e32 v12, 16, v13
	v_bfe_u32 v13, v15, 16, 1
	v_add3_u32 v13, v15, v13, s12
	v_and_or_b32 v12, v13, s15, v12
	s_waitcnt lgkmcnt(0)
	v_bfe_u32 v13, v16, 16, 1
	v_add3_u32 v13, v16, v13, s12
	v_bfe_u32 v14, v17, 16, 1
	v_lshrrev_b32_e32 v13, 16, v13
	v_add3_u32 v14, v17, v14, s12
	s_add_i32 s16, s58, s16
	v_and_or_b32 v13, v14, s15, v13
	v_lshl_add_u32 v16, s17, 6, v19
	v_mov_b64_e32 v[14:15], s[50:51]
	v_mad_i64_i32 v[14:15], s[24:25], v16, s41, v[14:15]
	s_ashr_i32 s17, s16, 31
	v_lshl_add_u64 v[14:15], s[16:17], 1, v[14:15]
	v_lshl_add_u64 v[14:15], v[14:15], 0, v[0:1]
	s_add_i32 s58, s58, s23
	global_store_dwordx4 v[14:15], v[10:13], off
	s_cmpk_lt_i32 s59, 0x48
	s_mov_b32 s60, s59
	s_waitcnt vmcnt(1)
	v_pk_mul_f32 v[8:9], v[8:9], v[28:29] op_sel_hi:[1,0]
	v_pk_mul_f32 v[6:7], v[6:7], v[28:29] op_sel_hi:[1,0]
	v_pk_mul_f32 v[4:5], v[4:5], v[30:31] op_sel_hi:[1,0]
	v_pk_mul_f32 v[2:3], v[2:3], v[30:31] op_sel_hi:[1,0]
	v_mov_b32_e32 v10, v2
	v_mov_b32_e32 v11, v3
	v_mov_b32_e32 v12, v4
	v_mov_b32_e32 v13, v5
	v_mov_b32_e32 v14, v6
	v_mov_b32_e32 v15, v7
	v_mov_b32_e32 v16, v8
	v_mov_b32_e32 v17, v9
	s_cbranch_scc0 .LBB0_1975
.LBB0_1971:
	s_barrier
	s_waitcnt vmcnt(1)
	ds_write2_b32 v22, v14, v15 offset1:1
	v_add_u32_e32 v14, 0x2080, v22
	s_add_i32 s59, s22, s60
	s_waitcnt vmcnt(0)
	ds_write2_b32 v14, v10, v11 offset1:1
	ds_write2_b32 v22, v16, v17 offset0:2 offset1:3
	v_add_u32_e32 v10, 0x2088, v22
	s_cmpk_gt_i32 s59, 0x47
	ds_write2_b32 v10, v12, v13 offset1:1
	s_cbranch_scc1 .LBB0_1970
	s_mul_hi_i32 s24, s59, 0x2aaaaaab
	s_lshr_b32 s16, s24, 31
	s_add_i32 s24, s24, s16
	v_lshl_or_b32 v2, s24, 6, v18
	v_add_u32_e32 v3, 0xfffffe00, v2
	v_lshrrev_b32_e32 v3, 5, v3
	v_mov_b32_e32 v4, s24
	v_cmp_gt_i32_e32 vcc, s33, v2
	v_mov_b32_e32 v28, 1.0
	v_mov_b32_e32 v30, 1.0
	v_mov_b32_e32 v9, 0
	v_mov_b32_e32 v8, 0
	v_cndmask_b32_e32 v3, v3, v4, vcc
	v_cndmask_b32_e32 v2, v21, v18, vcc
	v_mad_u64_u32 v[10:11], s[16:17], v3, s18, v[2:3]
	v_cmp_lt_i32_e32 vcc, -1, v10
	v_mov_b32_e32 v7, 0
	v_mov_b32_e32 v6, 0
	v_mov_b32_e32 v5, 0
	v_mov_b32_e32 v4, 0
	v_mov_b32_e32 v3, 0
	v_mov_b32_e32 v2, 0
	s_and_saveexec_b64 s[16:17], vcc
	s_cbranch_execz .LBB0_1969
	s_mulk_i32 s24, 0xfe80
	s_add_i32 s24, s24, s58
	v_add_u32_e32 v12, s24, v23
	v_mov_b64_e32 v[2:3], s[42:43]
	v_mov_b32_e32 v11, v1
	v_add_u32_e32 v8, 32, v12
	v_mad_i64_i32 v[4:5], s[24:25], v12, s86, v[2:3]
	v_lshlrev_b64 v[6:7], 2, v[10:11]
	v_mad_i64_i32 v[2:3], s[24:25], v8, s86, v[2:3]
	v_lshl_add_u64 v[4:5], v[4:5], 0, v[6:7]
	v_lshl_add_u64 v[2:3], v[2:3], 0, v[6:7]
	global_load_dwordx4 v[6:9], v[4:5], off
	s_nop 0
	global_load_dwordx4 v[2:5], v[2:3], off
	s_andn2_b64 vcc, exec, s[56:57]
	s_cbranch_vccnz .LBB0_1969
	v_ashrrev_i32_e32 v13, 31, v12
	v_lshl_add_u64 v[10:11], v[12:13], 2, s[48:49]
	global_load_dword v28, v[10:11], off
	s_nop 0
	global_load_dword v30, v[10:11], off offset:128
	s_branch .LBB0_1969

; DI unsigned pk2(float lo, float hi) { return (unsigned)f2bf(lo) | ((unsigned)f2bf(hi) << 16); }
;     DI bf16_t* z() const { return (bf16_t*)(ws + WS_Z); }
;     DI float* b1(int l, int v) const { return (float*)(ws + WS_B1) + (l * 2 + v) * 128; }
; template <class Map>
; DI void wconv(const float* __restrict__ W, int K, int Nsrc, const float* __restrict__ gain, bf16_t* __restrict__ dst, int Ndst, Map map, float* tile) {
;     ...
;     WCONV_LOAD(it, a0, a1);
;     for (;;) {
;         const int nit = it + gridDim.x;
;         __syncthreads();
; #pragma unroll
;         for (int e = 0; e < 4; ++e) { tile[kk0 * 65 + nn4 + e] = a0[e]; tile[(kk0 + 32) * 65 + nn4 + e] = a1[e]; }
;         if (nit < ntiles) WCONV_LOAD(nit, b0, b1);
;         __syncthreads();
;         { const int kt = it % nkt, nt = it / nkt, k0 = kt * 64, n0 = nt * 64;
;           const float* tp = tile + (8 * cw) * 65 + nw;
;           u32x4 w; w.x = pk2(tp[0], tp[65]); w.y = pk2(tp[2 * 65], tp[3 * 65]); w.z = pk2(tp[4 * 65], tp[5 * 65]); w.w = pk2(tp[6 * 65], tp[7 * 65]);
;           *(u32x4*)(dst + (size_t)(n0 + nw) * K + k0 + 8 * cw) = w; }
;         if (nit >= ntiles) break;
;         a0 = b0; a1 = b1; it = nit;
;     }
.LBB0_1985:
	s_waitcnt lgkmcnt(0)
	s_barrier
	ds_read2_b32 v[10:11], v22 offset1:65
	ds_read2_b32 v[12:13], v22 offset0:130 offset1:195
	s_ashr_i32 s16, s60, 31
	s_lshr_b32 s16, s16, 30
	s_add_i32 s16, s60, s16
	s_waitcnt lgkmcnt(1)
	v_bfe_u32 v0, v10, 16, 1
	v_add3_u32 v0, v10, v0, s12
	v_bfe_u32 v10, v11, 16, 1
	v_lshrrev_b32_e32 v0, 16, v0
	v_add3_u32 v10, v11, v10, s12
	v_and_or_b32 v10, v10, s15, v0
	s_waitcnt lgkmcnt(0)
	v_bfe_u32 v0, v12, 16, 1
	v_add3_u32 v0, v12, v0, s12
	v_add_u32_e32 v12, 0x400, v22
	ds_read2_b32 v[14:15], v12 offset0:4 offset1:69
	v_bfe_u32 v11, v13, 16, 1
	ds_read2_b32 v[16:17], v12 offset0:134 offset1:199
	v_lshrrev_b32_e32 v0, 16, v0
	v_add3_u32 v11, v13, v11, s12
	s_ashr_i32 s17, s16, 2
	v_and_or_b32 v11, v11, s15, v0
	s_waitcnt lgkmcnt(1)
	v_bfe_u32 v0, v14, 16, 1
	v_add3_u32 v0, v14, v0, s12
	v_bfe_u32 v12, v15, 16, 1
	v_lshl_add_u32 v14, s17, 6, v21
	s_lshl_b32 s16, s17, 8
	v_lshrrev_b32_e32 v0, 16, v0
	v_add3_u32 v12, v15, v12, s12
	v_ashrrev_i32_e32 v15, 31, v14
	s_sub_i32 s16, s58, s16
	v_and_or_b32 v12, v12, s15, v0
	s_waitcnt lgkmcnt(0)
	v_bfe_u32 v0, v16, 16, 1
	v_lshlrev_b64 v[14:15], 9, v[14:15]
	v_add3_u32 v0, v16, v0, s12
	v_bfe_u32 v13, v17, 16, 1
	v_lshl_add_u64 v[14:15], s[50:51], 0, v[14:15]
	s_ashr_i32 s17, s16, 31
	v_lshrrev_b32_e32 v0, 16, v0
	v_add3_u32 v13, v17, v13, s12
	v_lshl_add_u64 v[14:15], s[16:17], 1, v[14:15]
	v_mov_b32_e32 v19, v1
	v_and_or_b32 v13, v13, s15, v0
	v_lshl_add_u64 v[14:15], v[14:15], 0, v[18:19]
	s_add_i32 s58, s58, s23
	global_store_dwordx4 v[14:15], v[10:13], off
	s_cmp_lt_i32 s59, 64
	s_mov_b32 s60, s59
	s_waitcnt vmcnt(1)
	v_pk_mul_f32 v[8:9], v[8:9], v[28:29] op_sel_hi:[1,0]
	v_pk_mul_f32 v[6:7], v[6:7], v[28:29] op_sel_hi:[1,0]
	v_pk_mul_f32 v[4:5], v[4:5], v[30:31] op_sel_hi:[1,0]
	v_pk_mul_f32 v[2:3], v[2:3], v[30:31] op_sel_hi:[1,0]
	v_mov_b32_e32 v10, v2
	v_mov_b32_e32 v11, v3
	v_mov_b32_e32 v12, v4
	v_mov_b32_e32 v13, v5
	v_mov_b32_e32 v14, v6
	v_mov_b32_e32 v15, v7
	v_mov_b32_e32 v16, v8
	v_mov_b32_e32 v17, v9
	s_cbranch_scc0 .LBB0_1994
.LBB0_1986:
	v_add_u32_e32 v0, 0x2080, v23
	s_add_i32 s59, s22, s60
	s_barrier
	s_waitcnt vmcnt(1)
	ds_write2_b32 v23, v14, v15 offset1:1
	s_waitcnt vmcnt(0)
	ds_write2_b32 v0, v10, v11 offset1:1
	ds_write2_b32 v23, v16, v17 offset0:2 offset1:3
	v_add_u32_e32 v0, 0x2088, v23
	s_cmp_gt_i32 s59, 63
	ds_write2_b32 v0, v12, v13 offset1:1
	s_cbranch_scc1 .LBB0_1985
	s_ashr_i32 s16, s59, 31
	s_lshr_b32 s16, s16, 30
	s_add_i32 s16, s59, s16
	s_ashr_i32 s24, s16, 2
	v_lshl_or_b32 v0, s24, 6, v20
	v_cmp_lt_i32_e32 vcc, s85, v0
	v_lshlrev_b32_e32 v2, 1, v0
	s_and_saveexec_b64 s[16:17], vcc
	s_xor_b64 s[16:17], exec, s[16:17]
	v_add_u32_e32 v0, 0x7ffffc00, v2
	s_mov_b32 s25, 0x7fffff80
	v_and_or_b32 v0, v0, s25, v24
	s_andn2_saveexec_b64 s[16:17], s[16:17]
	s_movk_i32 s25, 0xff80
	v_and_or_b32 v0, v2, s25, v20
	s_or_b64 exec, exec, s[16:17]
	v_cmp_lt_i32_e32 vcc, -1, v0
	v_mov_b32_e32 v28, 1.0
	v_mov_b32_e32 v30, 1.0
	v_mov_b32_e32 v9, 0
	v_mov_b32_e32 v8, 0
	v_mov_b32_e32 v7, 0
	v_mov_b32_e32 v6, 0
	v_mov_b32_e32 v5, 0
	v_mov_b32_e32 v4, 0
	v_mov_b32_e32 v3, 0
	v_mov_b32_e32 v2, 0
	s_and_saveexec_b64 s[16:17], vcc
	s_cbranch_execz .LBB0_1984
	v_add_u32_e32 v2, s58, v25
	s_lshl_b32 s24, s24, 8
	v_subrev_u32_e32 v10, s24, v2
	v_add_u32_e32 v6, 32, v10
	v_ashrrev_i32_e32 v11, 31, v10
	v_ashrrev_i32_e32 v7, 31, v6
	v_lshlrev_b64 v[2:3], 12, v[10:11]
	v_lshlrev_b64 v[6:7], 12, v[6:7]
	v_lshl_add_u64 v[2:3], s[42:43], 0, v[2:3]
	v_lshlrev_b64 v[4:5], 2, v[0:1]
	v_lshl_add_u64 v[6:7], s[42:43], 0, v[6:7]
	v_lshl_add_u64 v[2:3], v[2:3], 0, v[4:5]
	v_lshl_add_u64 v[4:5], v[6:7], 0, v[4:5]
	global_load_dwordx4 v[6:9], v[2:3], off
	s_nop 0
	global_load_dwordx4 v[2:5], v[4:5], off
	s_andn2_b64 vcc, exec, s[56:57]
	s_cbranch_vccnz .LBB0_1984
	v_lshl_add_u64 v[10:11], v[10:11], 2, s[48:49]
	global_load_dword v28, v[10:11], off
	s_nop 0
	global_load_dword v30, v[10:11], off offset:128
	s_branch .LBB0_1984

; DI unsigned pk2(float lo, float hi) { return (unsigned)f2bf(lo) | ((unsigned)f2bf(hi) << 16); }
;     DI bf16_t* z() const { return (bf16_t*)(ws + WS_Z); }
;     DI float* b1(int l, int v) const { return (float*)(ws + WS_B1) + (l * 2 + v) * 128; }
; template <class Map>
; DI void wconv(const float* __restrict__ W, int K, int Nsrc, const float* __restrict__ gain, bf16_t* __restrict__ dst, int Ndst, Map map, float* tile) {
;     ...
;     WCONV_LOAD(it, a0, a1);
;     for (;;) {
;         const int nit = it + gridDim.x;
;         __syncthreads();
; #pragma unroll
;         for (int e = 0; e < 4; ++e) { tile[kk0 * 65 + nn4 + e] = a0[e]; tile[(kk0 + 32) * 65 + nn4 + e] = a1[e]; }
;         if (nit < ntiles) WCONV_LOAD(nit, b0, b1);
;         __syncthreads();
;         { const int kt = it % nkt, nt = it / nkt, k0 = kt * 64, n0 = nt * 64;
;           const float* tp = tile + (8 * cw) * 65 + nw;
;           u32x4 w; w.x = pk2(tp[0], tp[65]); w.y = pk2(tp[2 * 65], tp[3 * 65]); w.z = pk2(tp[4 * 65], tp[5 * 65]); w.w = pk2(tp[6 * 65], tp[7 * 65]);
;           *(u32x4*)(dst + (size_t)(n0 + nw) * K + k0 + 8 * cw) = w; }
;         if (nit >= ntiles) break;
;         a0 = b0; a1 = b1; it = nit;
;     }
.LBB0_2045:
	s_waitcnt lgkmcnt(0)
	s_barrier
	ds_read2_b32 v[10:11], v20 offset1:65
	s_ashr_i32 s16, s59, 31
	s_lshr_b32 s16, s16, 28
	s_add_i32 s16, s59, s16
	s_ashr_i32 s17, s16, 4
	s_waitcnt lgkmcnt(0)
	v_bfe_u32 v12, v10, 16, 1
	v_add3_u32 v10, v10, v12, s12
	ds_read2_b32 v[12:13], v20 offset0:130 offset1:195
	v_bfe_u32 v14, v11, 16, 1
	v_lshrrev_b32_e32 v10, 16, v10
	v_add3_u32 v11, v11, v14, s12
	v_and_or_b32 v10, v11, s15, v10
	s_waitcnt lgkmcnt(0)
	v_bfe_u32 v11, v12, 16, 1
	v_add3_u32 v11, v12, v11, s12
	v_add_u32_e32 v12, 0x400, v20
	ds_read2_b32 v[14:15], v12 offset0:4 offset1:69
	v_bfe_u32 v16, v13, 16, 1
	v_lshrrev_b32_e32 v11, 16, v11
	v_add3_u32 v13, v13, v16, s12
	ds_read2_b32 v[16:17], v12 offset0:134 offset1:199
	v_and_or_b32 v11, v13, s15, v11
	s_waitcnt lgkmcnt(1)
	v_bfe_u32 v13, v14, 16, 1
	v_add3_u32 v13, v14, v13, s12
	v_lshrrev_b32_e32 v12, 16, v13
	v_bfe_u32 v13, v15, 16, 1
	v_add3_u32 v13, v15, v13, s12
	v_and_or_b32 v12, v13, s15, v12
	s_waitcnt lgkmcnt(0)
	v_bfe_u32 v13, v16, 16, 1
	v_add3_u32 v13, v16, v13, s12
	v_bfe_u32 v14, v17, 16, 1
	v_lshrrev_b32_e32 v13, 16, v13
	v_add3_u32 v14, v17, v14, s12
	v_and_or_b32 v13, v14, s15, v13
	v_lshl_add_u32 v14, s17, 6, v19
	s_lshl_b32 s16, s17, 10
	v_ashrrev_i32_e32 v15, 31, v14
	s_sub_i32 s16, s55, s16
	v_lshlrev_b64 v[14:15], 11, v[14:15]
	v_lshl_add_u64 v[14:15], s[56:57], 0, v[14:15]
	s_ashr_i32 s17, s16, 31
	v_lshl_add_u64 v[14:15], s[16:17], 1, v[14:15]
	v_lshl_add_u64 v[14:15], v[14:15], 0, v[0:1]
	s_add_i32 s55, s55, s23
	global_store_dwordx4 v[14:15], v[10:13], off
	s_cmpk_lt_i32 s58, 0x580
	s_mov_b32 s59, s58
	s_waitcnt vmcnt(1)
	v_pk_mul_f32 v[8:9], v[8:9], v[28:29] op_sel_hi:[1,0]
	v_pk_mul_f32 v[6:7], v[6:7], v[28:29] op_sel_hi:[1,0]
	v_pk_mul_f32 v[4:5], v[4:5], v[30:31] op_sel_hi:[1,0]
	v_pk_mul_f32 v[2:3], v[2:3], v[30:31] op_sel_hi:[1,0]
	v_mov_b32_e32 v10, v2
	v_mov_b32_e32 v11, v3
	v_mov_b32_e32 v12, v4
	v_mov_b32_e32 v13, v5
	v_mov_b32_e32 v14, v6
	v_mov_b32_e32 v15, v7
	v_mov_b32_e32 v16, v8
	v_mov_b32_e32 v17, v9
	s_cbranch_scc0 .LBB0_2050
.LBB0_2046:
	s_barrier
	s_waitcnt vmcnt(1)
	ds_write2_b32 v21, v14, v15 offset1:1
	v_add_u32_e32 v14, 0x2080, v21
	s_add_i32 s58, s22, s59
	s_waitcnt vmcnt(0)
	ds_write2_b32 v14, v10, v11 offset1:1
	ds_write2_b32 v21, v16, v17 offset0:2 offset1:3
	v_add_u32_e32 v10, 0x2088, v21
	s_cmpk_gt_i32 s58, 0x57f
	ds_write2_b32 v10, v12, v13 offset1:1
	s_cbranch_scc1 .LBB0_2045
	s_ashr_i32 s16, s58, 31
	s_lshr_b32 s16, s16, 28
	s_add_i32 s16, s58, s16
	s_ashr_i32 s24, s16, 4
	s_lshl_b32 s16, s24, 6
	s_and_b32 s16, s16, 0xc0
	s_cmpk_lt_u32 s16, 0x80
	v_or_b32_e32 v2, s16, v18
	s_cselect_b64 vcc, -1, 0
	s_lshl_b32 s16, s24, 5
	s_and_b32 s16, s16, 0xffffff80
	v_or_b32_e32 v3, s16, v2
	s_addk_i32 s16, 0xa80
	v_add_u32_e32 v2, s16, v2
	v_cndmask_b32_e32 v10, v2, v3, vcc
	v_cmp_lt_i32_e32 vcc, -1, v10
	v_mov_b32_e32 v28, 1.0
	v_mov_b32_e32 v30, 1.0
	v_mov_b32_e32 v9, 0
	v_mov_b32_e32 v8, 0
	v_mov_b32_e32 v7, 0
	v_mov_b32_e32 v6, 0
	v_mov_b32_e32 v5, 0
	v_mov_b32_e32 v4, 0
	v_mov_b32_e32 v3, 0
	v_mov_b32_e32 v2, 0
	s_and_saveexec_b64 s[16:17], vcc
	s_cbranch_execz .LBB0_2044
	v_add_u32_e32 v2, s55, v22
	s_lshl_b32 s24, s24, 10
	v_subrev_u32_e32 v12, s24, v2
	v_mov_b64_e32 v[2:3], s[42:43]
	s_movk_i32 s60, 0x5800
	v_mov_b32_e32 v11, v1
	v_add_u32_e32 v8, 32, v12
	v_mad_i64_i32 v[4:5], s[24:25], v12, s60, v[2:3]
	v_lshlrev_b64 v[6:7], 2, v[10:11]
	v_mad_i64_i32 v[2:3], s[24:25], v8, s60, v[2:3]
	v_lshl_add_u64 v[4:5], v[4:5], 0, v[6:7]
	v_lshl_add_u64 v[2:3], v[2:3], 0, v[6:7]
	global_load_dwordx4 v[6:9], v[4:5], off
	s_nop 0
	global_load_dwordx4 v[2:5], v[2:3], off
	s_andn2_b64 vcc, exec, s[48:49]
	s_cbranch_vccnz .LBB0_2044
	v_ashrrev_i32_e32 v13, 31, v12
	v_lshl_add_u64 v[10:11], v[12:13], 2, s[50:51]
	global_load_dword v28, v[10:11], off
	s_nop 0
	global_load_dword v30, v[10:11], off offset:128
	s_branch .LBB0_2044
